# v32 + nt hint on the once-read f32 weight loads of the first-phase (P0) weight conversion
# baseline (speedup 1.0000x reference)
.LBB0_53:
	s_ashr_i32 s11, s10, 31
	s_lshr_b32 s11, s11, 25
	s_add_i32 s11, s10, s11
	s_ashr_i32 s11, s11, 7
	s_lshl_b32 s14, s11, 6
	s_lshl_b32 s11, s11, 12
	s_andn2_b64 vcc, exec, s[6:7]
	s_sub_i32 s11, 0, s11
	s_cbranch_vccnz .LBB0_55
	s_add_i32 s18, s9, s11
	v_or_b32_e32 v56, s14, v14
	s_ashr_i32 s19, s18, 31
	v_ashrrev_i32_e32 v57, 31, v56
	v_lshl_add_u64 v[58:59], s[18:19], 2, v[6:7]
	v_lshlrev_b64 v[10:11], 14, v[56:57]
	v_or_b32_e32 v32, 8, v56
	v_lshl_add_u64 v[10:11], v[58:59], 0, v[10:11]
	v_ashrrev_i32_e32 v33, 31, v32
	global_load_dwordx4 v[10:13], v[10:11], off nt
	v_lshlrev_b64 v[32:33], 14, v[32:33]
	v_or_b32_e32 v36, 16, v56
	v_lshl_add_u64 v[32:33], v[58:59], 0, v[32:33]
	v_ashrrev_i32_e32 v37, 31, v36
	global_load_dwordx4 v[32:35], v[32:33], off nt
	v_lshlrev_b64 v[36:37], 14, v[36:37]
	v_or_b32_e32 v40, 24, v56
	v_lshl_add_u64 v[36:37], v[58:59], 0, v[36:37]
	v_ashrrev_i32_e32 v41, 31, v40
	global_load_dwordx4 v[36:39], v[36:37], off nt
	v_lshlrev_b64 v[40:41], 14, v[40:41]
	v_or_b32_e32 v44, 32, v56
	v_lshl_add_u64 v[40:41], v[58:59], 0, v[40:41]
	v_ashrrev_i32_e32 v45, 31, v44
	global_load_dwordx4 v[40:43], v[40:41], off nt
	v_lshlrev_b64 v[44:45], 14, v[44:45]
	v_or_b32_e32 v48, 40, v56
	v_lshl_add_u64 v[44:45], v[58:59], 0, v[44:45]
	v_ashrrev_i32_e32 v49, 31, v48
	global_load_dwordx4 v[44:47], v[44:45], off nt
	v_lshlrev_b64 v[48:49], 14, v[48:49]
	v_or_b32_e32 v52, 48, v56
	v_lshl_add_u64 v[48:49], v[58:59], 0, v[48:49]
	v_ashrrev_i32_e32 v53, 31, v52
	global_load_dwordx4 v[48:51], v[48:49], off nt
	v_lshlrev_b64 v[52:53], 14, v[52:53]
	v_or_b32_e32 v56, 56, v56
	v_lshl_add_u64 v[52:53], v[58:59], 0, v[52:53]
	v_ashrrev_i32_e32 v57, 31, v56
	global_load_dwordx4 v[52:55], v[52:53], off nt
	v_lshlrev_b64 v[56:57], 14, v[56:57]
	v_lshl_add_u64 v[56:57], v[58:59], 0, v[56:57]
	global_load_dwordx4 v[56:59], v[56:57], off nt
	s_ashr_i32 s15, s14, 31
	s_waitcnt vmcnt(7)
	ds_write2_b32 v16, v10, v11 offset1:1
	ds_write2_b32 v16, v12, v13 offset0:2 offset1:3
	s_waitcnt vmcnt(6)
	ds_write2_b32 v17, v32, v33 offset1:1
	ds_write2_b32 v18, v34, v35 offset1:1
	s_waitcnt vmcnt(5)
	ds_write2_b32 v19, v36, v37 offset1:1
	ds_write2_b32 v20, v38, v39 offset1:1
	s_waitcnt vmcnt(4)
	ds_write2_b32 v21, v40, v41 offset1:1
	ds_write2_b32 v22, v42, v43 offset1:1
	s_waitcnt vmcnt(3)
	ds_write2_b32 v23, v44, v45 offset1:1
	ds_write2_b32 v24, v46, v47 offset1:1
	s_waitcnt vmcnt(2)
	ds_write2_b32 v25, v48, v49 offset1:1
	ds_write2_b32 v26, v50, v51 offset1:1
	s_waitcnt vmcnt(1)
	ds_write2_b32 v27, v52, v53 offset1:1
	ds_write2_b32 v28, v54, v55 offset1:1
	s_waitcnt vmcnt(0)
	ds_write2_b32 v29, v56, v57 offset1:1
	ds_write2_b32 v30, v58, v59 offset1:1
	s_waitcnt lgkmcnt(0)
	ds_read2_b32 v[36:37], v15 offset0:33 offset1:41
	ds_read2_b32 v[38:39], v15 offset1:8
	ds_read2_b32 v[40:41], v15 offset0:66 offset1:74
	ds_read2_b32 v[42:43], v15 offset0:99 offset1:107
	ds_read2_b32 v[44:45], v15 offset0:132 offset1:140
	ds_read2_b32 v[46:47], v15 offset0:165 offset1:173
	ds_read2_b32 v[48:49], v15 offset0:198 offset1:206
	ds_read2_b32 v[50:51], v15 offset0:231 offset1:239
	v_add_u32_e32 v12, s18, v14
	v_ashrrev_i32_e32 v13, 31, v12
	v_lshl_add_u64 v[10:11], s[14:15], 1, v[8:9]
	v_lshlrev_b64 v[52:53], 11, v[12:13]
	s_waitcnt lgkmcnt(6)
	v_cvt_pk_bf16_f32 v32, v38, v36
	s_waitcnt lgkmcnt(4)
	v_cvt_pk_bf16_f32 v33, v40, v42
	s_waitcnt lgkmcnt(2)
	v_cvt_pk_bf16_f32 v34, v44, v46
	s_waitcnt lgkmcnt(0)
	v_cvt_pk_bf16_f32 v35, v48, v50
	v_lshl_add_u64 v[52:53], v[10:11], 0, v[52:53]
	v_add_u32_e32 v36, 8, v12
	global_store_dwordx4 v[52:53], v[32:35], off
	v_add_u32_e32 v52, 16, v12
	v_ashrrev_i32_e32 v53, 31, v52
	v_cvt_pk_bf16_f32 v32, v39, v37
	v_ashrrev_i32_e32 v37, 31, v36
	v_lshlrev_b64 v[36:37], 11, v[36:37]
	v_cvt_pk_bf16_f32 v33, v41, v43
	v_cvt_pk_bf16_f32 v34, v45, v47
	v_cvt_pk_bf16_f32 v35, v49, v51
	v_lshl_add_u64 v[36:37], v[10:11], 0, v[36:37]
	global_store_dwordx4 v[36:37], v[32:35], off
	ds_read2_b32 v[36:37], v15 offset0:49 offset1:57
	ds_read2_b32 v[38:39], v15 offset0:16 offset1:24
	ds_read2_b32 v[40:41], v15 offset0:82 offset1:90
	ds_read2_b32 v[42:43], v15 offset0:115 offset1:123
	ds_read2_b32 v[44:45], v15 offset0:148 offset1:156
	ds_read2_b32 v[46:47], v15 offset0:181 offset1:189
	ds_read2_b32 v[48:49], v15 offset0:214 offset1:222
	ds_read2_b32 v[50:51], v15 offset0:247 offset1:255
	v_add_u32_e32 v12, 24, v12
	v_lshlrev_b64 v[52:53], 11, v[52:53]
	v_ashrrev_i32_e32 v13, 31, v12
	s_waitcnt lgkmcnt(6)
	v_cvt_pk_bf16_f32 v32, v38, v36
	s_waitcnt lgkmcnt(4)
	v_cvt_pk_bf16_f32 v33, v40, v42
	s_waitcnt lgkmcnt(2)
	v_cvt_pk_bf16_f32 v34, v44, v46
	s_waitcnt lgkmcnt(0)
	v_cvt_pk_bf16_f32 v35, v48, v50
	v_lshl_add_u64 v[52:53], v[10:11], 0, v[52:53]
	v_lshlrev_b64 v[12:13], 11, v[12:13]
	global_store_dwordx4 v[52:53], v[32:35], off
	v_lshl_add_u64 v[10:11], v[10:11], 0, v[12:13]
	s_nop 0
	v_cvt_pk_bf16_f32 v32, v39, v37
	v_cvt_pk_bf16_f32 v33, v41, v43
	v_cvt_pk_bf16_f32 v34, v45, v47
	v_cvt_pk_bf16_f32 v35, v49, v51
	global_store_dwordx4 v[10:11], v[32:35], off
	s_waitcnt lgkmcnt(0)
	s_cbranch_execnz .LBB0_52
	s_branch .LBB0_51

.LBB0_58:
	s_mul_hi_i32 s10, s5, 0x2aaaaaab
	s_lshr_b32 s11, s10, 31
	s_ashr_i32 s10, s10, 3
	s_add_i32 s10, s10, s11
	s_lshl_b32 s18, s10, 6
	s_andn2_b64 vcc, exec, s[14:15]
	s_mulk_i32 s10, 0xfa00
	s_cbranch_vccnz .LBB0_60
	s_add_i32 s24, s8, s10
	s_ashr_i32 s25, s24, 31
	v_or_b32_e32 v38, s18, v10
	v_lshl_add_u64 v[36:37], s[24:25], 2, v[2:3]
	v_mad_i64_i32 v[6:7], s[12:13], v38, s76, v[36:37]
	v_or_b32_e32 v12, 8, v38
	global_load_dwordx4 v[6:9], v[6:7], off nt
	v_mad_i64_i32 v[12:13], s[12:13], v12, s76, v[36:37]
	global_load_dwordx4 v[12:15], v[12:13], off nt
	s_waitcnt vmcnt(2)
	v_or_b32_e32 v16, 16, v38
	v_mad_i64_i32 v[16:17], s[12:13], v16, s76, v[36:37]
	global_load_dwordx4 v[16:19], v[16:17], off nt
	v_or_b32_e32 v20, 24, v38
	v_mad_i64_i32 v[20:21], s[12:13], v20, s76, v[36:37]
	global_load_dwordx4 v[20:23], v[20:21], off nt
	v_or_b32_e32 v24, 32, v38
	v_mad_i64_i32 v[24:25], s[12:13], v24, s76, v[36:37]
	global_load_dwordx4 v[24:27], v[24:25], off nt
	v_or_b32_e32 v28, 40, v38
	v_mad_i64_i32 v[28:29], s[12:13], v28, s76, v[36:37]
	global_load_dwordx4 v[28:31], v[28:29], off nt
	v_or_b32_e32 v32, 48, v38
	v_mad_i64_i32 v[32:33], s[12:13], v32, s76, v[36:37]
	global_load_dwordx4 v[32:35], v[32:33], off nt
	v_or_b32_e32 v38, 56, v38
	v_mad_i64_i32 v[36:37], s[12:13], v38, s76, v[36:37]
	global_load_dwordx4 v[36:39], v[36:37], off nt
	s_ashr_i32 s19, s18, 31
	s_waitcnt vmcnt(7)
	ds_write2_b32 v11, v6, v7 offset1:1
	ds_write2_b32 v11, v8, v9 offset0:2 offset1:3
	v_add_u32_e32 v6, 0x420, v11
	v_add_u32_e32 v8, s24, v10
	s_waitcnt vmcnt(6)
	ds_write2_b32 v6, v12, v13 offset1:1
	v_add_u32_e32 v6, 0x428, v11
	ds_write2_b32 v6, v14, v15 offset1:1
	v_add_u32_e32 v6, 0x840, v11
	s_waitcnt vmcnt(5)
	ds_write2_b32 v6, v16, v17 offset1:1
	v_add_u32_e32 v6, 0x848, v11
	ds_write2_b32 v6, v18, v19 offset1:1
	v_add_u32_e32 v6, 0xc60, v11
	s_waitcnt vmcnt(4)
	ds_write2_b32 v6, v20, v21 offset1:1
	v_add_u32_e32 v6, 0xc68, v11
	ds_write2_b32 v6, v22, v23 offset1:1
	v_add_u32_e32 v6, 0x1080, v11
	s_waitcnt vmcnt(3)
	ds_write2_b32 v6, v24, v25 offset1:1
	v_add_u32_e32 v6, 0x1088, v11
	ds_write2_b32 v6, v26, v27 offset1:1
	v_add_u32_e32 v6, 0x14a0, v11
	s_waitcnt vmcnt(2)
	ds_write2_b32 v6, v28, v29 offset1:1
	v_add_u32_e32 v6, 0x14a8, v11
	ds_write2_b32 v6, v30, v31 offset1:1
	v_add_u32_e32 v6, 0x18c0, v11
	s_waitcnt vmcnt(1)
	ds_write2_b32 v6, v32, v33 offset1:1
	v_add_u32_e32 v6, 0x18c8, v11
	ds_write2_b32 v6, v34, v35 offset1:1
	v_add_u32_e32 v6, 0x1ce0, v11
	s_waitcnt vmcnt(0)
	ds_write2_b32 v6, v36, v37 offset1:1
	v_add_u32_e32 v6, 0x1ce8, v11
	ds_write2_b32 v6, v38, v39 offset1:1
	s_waitcnt lgkmcnt(0)
	ds_read2_b32 v[16:17], v0 offset0:33 offset1:41
	ds_read2_b32 v[18:19], v0 offset1:8
	ds_read2_b32 v[20:21], v0 offset0:66 offset1:74
	ds_read2_b32 v[22:23], v0 offset0:99 offset1:107
	ds_read2_b32 v[24:25], v0 offset0:132 offset1:140
	ds_read2_b32 v[26:27], v0 offset0:165 offset1:173
	ds_read2_b32 v[28:29], v0 offset0:198 offset1:206
	ds_read2_b32 v[30:31], v0 offset0:231 offset1:239
	v_ashrrev_i32_e32 v9, 31, v8
	v_lshl_add_u64 v[6:7], s[18:19], 1, v[4:5]
	v_lshlrev_b64 v[32:33], 11, v[8:9]
	s_waitcnt lgkmcnt(6)
	v_cvt_pk_bf16_f32 v12, v18, v16
	s_waitcnt lgkmcnt(4)
	v_cvt_pk_bf16_f32 v13, v20, v22
	s_waitcnt lgkmcnt(2)
	v_cvt_pk_bf16_f32 v14, v24, v26
	s_waitcnt lgkmcnt(0)
	v_cvt_pk_bf16_f32 v15, v28, v30
	v_lshl_add_u64 v[32:33], v[6:7], 0, v[32:33]
	v_add_u32_e32 v16, 8, v8
	global_store_dwordx4 v[32:33], v[12:15], off
	v_add_u32_e32 v32, 16, v8
	v_ashrrev_i32_e32 v33, 31, v32
	v_cvt_pk_bf16_f32 v12, v19, v17
	v_ashrrev_i32_e32 v17, 31, v16
	v_lshlrev_b64 v[16:17], 11, v[16:17]
	v_cvt_pk_bf16_f32 v13, v21, v23
	v_cvt_pk_bf16_f32 v14, v25, v27
	v_cvt_pk_bf16_f32 v15, v29, v31
	v_lshl_add_u64 v[16:17], v[6:7], 0, v[16:17]
	global_store_dwordx4 v[16:17], v[12:15], off
	ds_read2_b32 v[16:17], v0 offset0:49 offset1:57
	ds_read2_b32 v[18:19], v0 offset0:16 offset1:24
	ds_read2_b32 v[20:21], v0 offset0:82 offset1:90
	ds_read2_b32 v[22:23], v0 offset0:115 offset1:123
	ds_read2_b32 v[24:25], v0 offset0:148 offset1:156
	ds_read2_b32 v[26:27], v0 offset0:181 offset1:189
	ds_read2_b32 v[28:29], v0 offset0:214 offset1:222
	ds_read2_b32 v[30:31], v0 offset0:247 offset1:255
	v_add_u32_e32 v8, 24, v8
	v_lshlrev_b64 v[32:33], 11, v[32:33]
	v_ashrrev_i32_e32 v9, 31, v8
	s_waitcnt lgkmcnt(6)
	v_cvt_pk_bf16_f32 v12, v18, v16
	s_waitcnt lgkmcnt(4)
	v_cvt_pk_bf16_f32 v13, v20, v22
	s_waitcnt lgkmcnt(2)
	v_cvt_pk_bf16_f32 v14, v24, v26
	s_waitcnt lgkmcnt(0)
	v_cvt_pk_bf16_f32 v15, v28, v30
	v_lshl_add_u64 v[32:33], v[6:7], 0, v[32:33]
	v_lshlrev_b64 v[8:9], 11, v[8:9]
	global_store_dwordx4 v[32:33], v[12:15], off
	v_lshl_add_u64 v[6:7], v[6:7], 0, v[8:9]
	s_nop 0
	v_cvt_pk_bf16_f32 v12, v19, v17
	v_cvt_pk_bf16_f32 v13, v21, v23
	v_cvt_pk_bf16_f32 v14, v25, v27
	v_cvt_pk_bf16_f32 v15, v29, v31
	global_store_dwordx4 v[6:7], v[12:15], off
	s_waitcnt lgkmcnt(0)
	s_cbranch_execnz .LBB0_57
	s_branch .LBB0_56

.LBB0_69:
	s_ashr_i32 s0, s4, 31
	s_lshr_b32 s0, s0, 27
	s_add_i32 s0, s4, s0
	s_ashr_i32 s1, s0, 5
	s_lshl_b32 s0, s1, 6
	s_lshl_b32 s1, s1, 10
	s_andn2_b64 vcc, exec, s[6:7]
	s_sub_i32 s9, 0, s1
	s_cbranch_vccnz .LBB0_71
	s_add_i32 s14, s5, s9
	v_or_b32_e32 v52, s0, v14
	s_ashr_i32 s15, s14, 31
	v_ashrrev_i32_e32 v53, 31, v52
	v_lshl_add_u64 v[54:55], s[14:15], 2, v[4:5]
	v_lshlrev_b64 v[6:7], 12, v[52:53]
	v_or_b32_e32 v10, 8, v52
	v_lshl_add_u64 v[6:7], v[54:55], 0, v[6:7]
	v_ashrrev_i32_e32 v11, 31, v10
	global_load_dwordx4 v[6:9], v[6:7], off nt
	v_lshlrev_b64 v[10:11], 12, v[10:11]
	v_or_b32_e32 v32, 16, v52
	v_lshl_add_u64 v[10:11], v[54:55], 0, v[10:11]
	v_ashrrev_i32_e32 v33, 31, v32
	global_load_dwordx4 v[10:13], v[10:11], off nt
	v_lshlrev_b64 v[32:33], 12, v[32:33]
	v_or_b32_e32 v36, 24, v52
	v_lshl_add_u64 v[32:33], v[54:55], 0, v[32:33]
	v_ashrrev_i32_e32 v37, 31, v36
	global_load_dwordx4 v[32:35], v[32:33], off nt
	v_lshlrev_b64 v[36:37], 12, v[36:37]
	v_or_b32_e32 v40, 32, v52
	v_lshl_add_u64 v[36:37], v[54:55], 0, v[36:37]
	v_ashrrev_i32_e32 v41, 31, v40
	global_load_dwordx4 v[36:39], v[36:37], off nt
	v_lshlrev_b64 v[40:41], 12, v[40:41]
	v_or_b32_e32 v44, 40, v52
	v_lshl_add_u64 v[40:41], v[54:55], 0, v[40:41]
	v_ashrrev_i32_e32 v45, 31, v44
	global_load_dwordx4 v[40:43], v[40:41], off nt
	v_lshlrev_b64 v[44:45], 12, v[44:45]
	v_or_b32_e32 v48, 48, v52
	v_lshl_add_u64 v[44:45], v[54:55], 0, v[44:45]
	v_ashrrev_i32_e32 v49, 31, v48
	global_load_dwordx4 v[44:47], v[44:45], off nt
	v_lshlrev_b64 v[48:49], 12, v[48:49]
	v_or_b32_e32 v52, 56, v52
	v_lshl_add_u64 v[48:49], v[54:55], 0, v[48:49]
	v_ashrrev_i32_e32 v53, 31, v52
	global_load_dwordx4 v[48:51], v[48:49], off nt
	v_lshlrev_b64 v[52:53], 12, v[52:53]
	v_lshl_add_u64 v[52:53], v[54:55], 0, v[52:53]
	global_load_dwordx4 v[52:55], v[52:53], off nt
	s_ashr_i32 s1, s0, 31
	s_waitcnt vmcnt(7)
	ds_write2_b32 v16, v6, v7 offset1:1
	ds_write2_b32 v16, v8, v9 offset0:2 offset1:3
	s_waitcnt vmcnt(6)
	ds_write2_b32 v17, v10, v11 offset1:1
	ds_write2_b32 v18, v12, v13 offset1:1
	s_waitcnt vmcnt(5)
	ds_write2_b32 v19, v32, v33 offset1:1
	ds_write2_b32 v20, v34, v35 offset1:1
	s_waitcnt vmcnt(4)
	ds_write2_b32 v21, v36, v37 offset1:1
	ds_write2_b32 v22, v38, v39 offset1:1
	s_waitcnt vmcnt(3)
	ds_write2_b32 v23, v40, v41 offset1:1
	ds_write2_b32 v24, v42, v43 offset1:1
	s_waitcnt vmcnt(2)
	ds_write2_b32 v25, v44, v45 offset1:1
	ds_write2_b32 v26, v46, v47 offset1:1
	s_waitcnt vmcnt(1)
	ds_write2_b32 v27, v48, v49 offset1:1
	ds_write2_b32 v28, v50, v51 offset1:1
	s_waitcnt vmcnt(0)
	ds_write2_b32 v29, v52, v53 offset1:1
	ds_write2_b32 v30, v54, v55 offset1:1
	s_waitcnt lgkmcnt(0)
	ds_read2_b32 v[32:33], v15 offset0:33 offset1:41
	ds_read2_b32 v[34:35], v15 offset1:8
	ds_read2_b32 v[36:37], v15 offset0:66 offset1:74
	ds_read2_b32 v[38:39], v15 offset0:99 offset1:107
	ds_read2_b32 v[40:41], v15 offset0:132 offset1:140
	ds_read2_b32 v[42:43], v15 offset0:165 offset1:173
	ds_read2_b32 v[44:45], v15 offset0:198 offset1:206
	ds_read2_b32 v[46:47], v15 offset0:231 offset1:239
	v_add_u32_e32 v8, s14, v14
	v_ashrrev_i32_e32 v9, 31, v8
	v_lshl_add_u64 v[6:7], s[0:1], 1, v[2:3]
	v_lshlrev_b64 v[48:49], 13, v[8:9]
	s_waitcnt lgkmcnt(6)
	v_cvt_pk_bf16_f32 v10, v34, v32
	s_waitcnt lgkmcnt(4)
	v_cvt_pk_bf16_f32 v11, v36, v38
	s_waitcnt lgkmcnt(2)
	v_cvt_pk_bf16_f32 v12, v40, v42
	s_waitcnt lgkmcnt(0)
	v_cvt_pk_bf16_f32 v13, v44, v46
	v_lshl_add_u64 v[48:49], v[6:7], 0, v[48:49]
	v_add_u32_e32 v32, 8, v8
	global_store_dwordx4 v[48:49], v[10:13], off
	v_add_u32_e32 v48, 16, v8
	v_ashrrev_i32_e32 v49, 31, v48
	v_cvt_pk_bf16_f32 v10, v35, v33
	v_ashrrev_i32_e32 v33, 31, v32
	v_lshlrev_b64 v[32:33], 13, v[32:33]
	v_cvt_pk_bf16_f32 v11, v37, v39
	v_cvt_pk_bf16_f32 v12, v41, v43
	v_cvt_pk_bf16_f32 v13, v45, v47
	v_lshl_add_u64 v[32:33], v[6:7], 0, v[32:33]
	global_store_dwordx4 v[32:33], v[10:13], off
	ds_read2_b32 v[32:33], v15 offset0:49 offset1:57
	ds_read2_b32 v[34:35], v15 offset0:16 offset1:24
	ds_read2_b32 v[36:37], v15 offset0:82 offset1:90
	ds_read2_b32 v[38:39], v15 offset0:115 offset1:123
	ds_read2_b32 v[40:41], v15 offset0:148 offset1:156
	ds_read2_b32 v[42:43], v15 offset0:181 offset1:189
	ds_read2_b32 v[44:45], v15 offset0:214 offset1:222
	ds_read2_b32 v[46:47], v15 offset0:247 offset1:255
	v_add_u32_e32 v8, 24, v8
	v_lshlrev_b64 v[48:49], 13, v[48:49]
	v_ashrrev_i32_e32 v9, 31, v8
	s_waitcnt lgkmcnt(6)
	v_cvt_pk_bf16_f32 v10, v34, v32
	s_waitcnt lgkmcnt(4)
	v_cvt_pk_bf16_f32 v11, v36, v38
	s_waitcnt lgkmcnt(2)
	v_cvt_pk_bf16_f32 v12, v40, v42
	s_waitcnt lgkmcnt(0)
	v_cvt_pk_bf16_f32 v13, v44, v46
	v_lshl_add_u64 v[48:49], v[6:7], 0, v[48:49]
	v_lshlrev_b64 v[8:9], 13, v[8:9]
	global_store_dwordx4 v[48:49], v[10:13], off
	v_lshl_add_u64 v[6:7], v[6:7], 0, v[8:9]
	s_nop 0
	v_cvt_pk_bf16_f32 v10, v35, v33
	v_cvt_pk_bf16_f32 v11, v37, v39
	v_cvt_pk_bf16_f32 v12, v41, v43
	v_cvt_pk_bf16_f32 v13, v45, v47
	global_store_dwordx4 v[6:7], v[10:13], off
	s_waitcnt lgkmcnt(0)
	s_cbranch_execnz .LBB0_68
	s_branch .LBB0_67
